# static s_setprio 1 for waves 4-7 also in the MIX1 (scan workgroups) attention copy
# speedup vs baseline: 1.0121x; 1.0006x over previous
.LBB0_358:
	v_and_b32_e32 v197, 63, v201
	s_lshl_b32 s44, s18, 6
	v_cmp_gt_u32_e32 vcc, 32, v197
	v_lshlrev_b32_e32 v214, 3, v3
	s_cmp_gt_u32 s20, 4
	v_cndmask_b32_e64 v212, 0, 1.0, vcc
	s_waitcnt lgkmcnt(0)
	s_barrier
	s_cbranch_scc1 .LBB0_393
	v_writelane_b32 v255, s48, 0
	v_mul_f32_e32 v200, 0x3fb8aa3b, v2
	s_add_i32 s46, s45, 0xffffff80
	v_writelane_b32 v255, s49, 1
	s_add_i32 s47, s45, 0xbf
	s_add_i32 s48, s45, 0xffffffbf
	s_add_i32 s49, s45, 0x41
	v_lshlrev_b32_e32 v2, 2, v3
	v_lshrrev_b32_e32 v3, 2, v201
	s_lshl_b32 s6, s24, 1
	v_and_or_b32 v215, v3, 3, v2
	v_lshlrev_b32_e32 v3, 2, v201
	s_add_u32 s6, s82, s6
	v_and_b32_e32 v16, 16, v201
	v_and_b32_e32 v17, 12, v3
	v_sub_u32_e32 v2, v2, v203
	s_addc_u32 s7, s83, 0
	v_mov_b32_e32 v14, v1
	v_mov_b32_e32 v15, v1
	v_add_u32_e32 v217, 0x80, v2
	v_lshl_add_u64 v[198:199], s[6:7], 0, v[0:1]
	v_mov_b32_e32 v0, v1
	v_mov_b32_e32 v2, v1
	v_mov_b32_e32 v3, v1
	v_mov_b32_e32 v4, v1
	v_mov_b32_e32 v5, v1
	v_mov_b32_e32 v6, v1
	v_mov_b32_e32 v7, v1
	v_mov_b32_e32 v8, v1
	v_mov_b32_e32 v9, v1
	v_mov_b32_e32 v10, v1
	v_mov_b32_e32 v11, v1
	v_mov_b32_e32 v12, v1
	v_mov_b32_e32 v13, v1
	v_lshlrev_b32_e32 v222, 1, v16
	v_lshlrev_b32_e32 v223, 1, v17
	v_mov_b64_e32 v[78:79], v[14:15]
	v_mov_b64_e32 v[46:47], v[14:15]
	v_mov_b64_e32 v[62:63], v[14:15]
	v_mov_b64_e32 v[30:31], v[14:15]
	s_mov_b32 s61, 0
	v_mov_b32_e32 v216, v212
	v_mov_b32_e32 v202, v200
	v_mov_b64_e32 v[76:77], v[12:13]
	v_mov_b64_e32 v[74:75], v[10:11]
	v_mov_b64_e32 v[72:73], v[8:9]
	v_mov_b64_e32 v[70:71], v[6:7]
	v_mov_b64_e32 v[68:69], v[4:5]
	v_mov_b64_e32 v[66:67], v[2:3]
	v_mov_b64_e32 v[64:65], v[0:1]
	v_mov_b64_e32 v[44:45], v[12:13]
	v_mov_b64_e32 v[42:43], v[10:11]
	v_mov_b64_e32 v[40:41], v[8:9]
	v_mov_b64_e32 v[38:39], v[6:7]
	v_mov_b64_e32 v[36:37], v[4:5]
	v_mov_b64_e32 v[34:35], v[2:3]
	v_mov_b64_e32 v[32:33], v[0:1]
	v_mov_b64_e32 v[60:61], v[12:13]
	v_mov_b64_e32 v[58:59], v[10:11]
	v_mov_b64_e32 v[56:57], v[8:9]
	v_mov_b64_e32 v[54:55], v[6:7]
	v_mov_b64_e32 v[52:53], v[4:5]
	v_mov_b64_e32 v[50:51], v[2:3]
	v_mov_b64_e32 v[48:49], v[0:1]
	v_mov_b64_e32 v[28:29], v[12:13]
	v_mov_b64_e32 v[26:27], v[10:11]
	v_mov_b64_e32 v[24:25], v[8:9]
	v_mov_b64_e32 v[22:23], v[6:7]
	v_mov_b64_e32 v[20:21], v[4:5]
	v_mov_b64_e32 v[18:19], v[2:3]
	v_mov_b64_e32 v[16:17], v[0:1]
	v_readfirstlane_b32 s99, v244
	s_lshr_b32 s99, s99, 8
	s_cmp_eq_u32 s99, 1
	s_cbranch_scc0 .Lap_skip_mix1
	s_setprio 1
.Lap_skip_mix1:
.LBB0_360:
	s_cmp_lt_i32 s39, 5
	s_cselect_b64 s[6:7], -1, 0
	s_cmp_gt_i32 s39, 4
	s_cselect_b64 s[14:15], -1, 0
	s_mov_b32 s62, 5
	s_and_b64 vcc, exec, s[14:15]
	s_cbranch_vccnz .LBB0_369
	s_lshl_b32 s18, s39, 7
	s_mov_b32 s62, s39
	s_branch .LBB0_363

.LBB0_395:
	s_setprio 0
	v_mov_b32_e32 v0, v216
	s_nop 1
	v_permlane32_swap_b32_e32 v216, v0
	v_add_f32_e32 v0, v216, v0
	v_div_scale_f32 v2, s[4:5], v0, v0, 1.0
	v_rcp_f32_e32 v3, v2
	s_mulk_i32 s29, 0x2400
	s_add_i32 s6, s29, 0
	v_mov_b32_e32 v13, s28
	v_fma_f32 v4, -v2, v3, 1.0
	v_fmac_f32_e32 v3, v4, v3
	v_div_scale_f32 v4, vcc, 1.0, v0, 1.0
	v_mul_f32_e32 v5, v4, v3
	v_fma_f32 v6, -v2, v5, v4
	v_fmac_f32_e32 v5, v6, v3
	v_fma_f32 v2, -v2, v5, v4
	v_div_fmas_f32 v2, v2, v3, v5
	v_div_fixup_f32 v0, v2, v0, 1.0
	v_mul_u32_u24_e32 v2, 0x90, v203
	v_add3_u32 v4, s6, v214, v2
	v_mul_f32_e32 v2, v64, v0
	v_mul_f32_e32 v3, v65, v0
	v_cvt_pk_bf16_f32 v2, v2, v3
	v_mul_f32_e32 v3, v66, v0
	v_mul_f32_e32 v5, v67, v0
	v_cvt_pk_bf16_f32 v3, v3, v5
	ds_write_b64 v4, v[2:3]
	v_mul_f32_e32 v2, v68, v0
	v_mul_f32_e32 v3, v69, v0
	v_cvt_pk_bf16_f32 v2, v2, v3
	v_mul_f32_e32 v3, v70, v0
	v_mul_f32_e32 v5, v71, v0
	v_cvt_pk_bf16_f32 v3, v3, v5
	ds_write_b64 v4, v[2:3] offset:16
	v_mul_f32_e32 v2, v72, v0
	v_mul_f32_e32 v3, v73, v0
	v_cvt_pk_bf16_f32 v2, v2, v3
	v_mul_f32_e32 v3, v74, v0
	v_mul_f32_e32 v5, v75, v0
	v_cvt_pk_bf16_f32 v3, v3, v5
	ds_write_b64 v4, v[2:3] offset:32
	v_mul_f32_e32 v2, v76, v0
	v_mul_f32_e32 v3, v77, v0
	v_cvt_pk_bf16_f32 v2, v2, v3
	v_mul_f32_e32 v3, v78, v0
	v_mul_f32_e32 v5, v79, v0
	v_cvt_pk_bf16_f32 v3, v3, v5
	ds_write_b64 v4, v[2:3] offset:48
	v_mul_f32_e32 v2, v48, v0
	v_mul_f32_e32 v3, v49, v0
	v_cvt_pk_bf16_f32 v2, v2, v3
	v_mul_f32_e32 v3, v50, v0
	v_mul_f32_e32 v5, v51, v0
	v_cvt_pk_bf16_f32 v3, v3, v5
	ds_write_b64 v4, v[2:3] offset:64
	v_mul_f32_e32 v2, v52, v0
	v_mul_f32_e32 v3, v53, v0
	v_cvt_pk_bf16_f32 v2, v2, v3
	v_mul_f32_e32 v3, v54, v0
	v_mul_f32_e32 v5, v55, v0
	v_cvt_pk_bf16_f32 v3, v3, v5
	ds_write_b64 v4, v[2:3] offset:80
	v_mul_f32_e32 v2, v56, v0
	v_mul_f32_e32 v3, v57, v0
	v_cvt_pk_bf16_f32 v2, v2, v3
	v_mul_f32_e32 v3, v58, v0
	v_mul_f32_e32 v5, v59, v0
	v_cvt_pk_bf16_f32 v3, v3, v5
	v_mov_b32_e32 v5, v212
	s_nop 1
	v_permlane32_swap_b32_e32 v212, v5
	v_add_f32_e32 v5, v212, v5
	v_div_scale_f32 v6, s[4:5], v5, v5, 1.0
	v_rcp_f32_e32 v7, v6
	ds_write_b64 v4, v[2:3] offset:96
	v_mul_f32_e32 v2, v60, v0
	v_mul_f32_e32 v3, v61, v0
	v_cvt_pk_bf16_f32 v2, v2, v3
	v_mul_f32_e32 v3, v62, v0
	v_mul_f32_e32 v0, v63, v0
	v_cvt_pk_bf16_f32 v3, v3, v0
	v_fma_f32 v0, -v6, v7, 1.0
	v_fmac_f32_e32 v7, v0, v7
	v_div_scale_f32 v0, vcc, 1.0, v5, 1.0
	ds_write_b64 v4, v[2:3] offset:112
	v_mul_f32_e32 v2, v0, v7
	v_fma_f32 v3, -v6, v2, v0
	v_fmac_f32_e32 v2, v3, v7
	v_fma_f32 v0, -v6, v2, v0
	v_div_fmas_f32 v0, v0, v7, v2
	v_div_fixup_f32 v0, v0, v5, 1.0
	v_mul_f32_e32 v2, v32, v0
	v_mul_f32_e32 v3, v33, v0
	v_cvt_pk_bf16_f32 v2, v2, v3
	v_mul_f32_e32 v3, v34, v0
	v_mul_f32_e32 v5, v35, v0
	v_cvt_pk_bf16_f32 v3, v3, v5
	ds_write_b64 v4, v[2:3] offset:4608
	v_mul_f32_e32 v2, v36, v0
	v_mul_f32_e32 v3, v37, v0
	v_cvt_pk_bf16_f32 v2, v2, v3
	v_mul_f32_e32 v3, v38, v0
	v_mul_f32_e32 v5, v39, v0
	v_cvt_pk_bf16_f32 v3, v3, v5
	ds_write_b64 v4, v[2:3] offset:4624
	v_mul_f32_e32 v2, v40, v0
	v_mul_f32_e32 v3, v41, v0
	v_cvt_pk_bf16_f32 v2, v2, v3
	v_mul_f32_e32 v3, v42, v0
	v_mul_f32_e32 v5, v43, v0
	v_cvt_pk_bf16_f32 v3, v3, v5
	ds_write_b64 v4, v[2:3] offset:4640
	v_mul_f32_e32 v2, v44, v0
	v_mul_f32_e32 v3, v45, v0
	v_cvt_pk_bf16_f32 v2, v2, v3
	v_mul_f32_e32 v3, v46, v0
	v_mul_f32_e32 v5, v47, v0
	v_cvt_pk_bf16_f32 v3, v3, v5
	ds_write_b64 v4, v[2:3] offset:4656
	v_mul_f32_e32 v2, v16, v0
	v_mul_f32_e32 v3, v17, v0
	v_cvt_pk_bf16_f32 v2, v2, v3
	v_mul_f32_e32 v3, v18, v0
	v_mul_f32_e32 v5, v19, v0
	v_cvt_pk_bf16_f32 v3, v3, v5
	ds_write_b64 v4, v[2:3] offset:4672
	v_mul_f32_e32 v2, v20, v0
	v_mul_f32_e32 v3, v21, v0
	v_cvt_pk_bf16_f32 v2, v2, v3
	v_mul_f32_e32 v3, v22, v0
	v_mul_f32_e32 v5, v23, v0
	v_cvt_pk_bf16_f32 v3, v3, v5
	ds_write_b64 v4, v[2:3] offset:4688
	v_mul_f32_e32 v2, v24, v0
	v_mul_f32_e32 v3, v25, v0
	v_cvt_pk_bf16_f32 v2, v2, v3
	v_mul_f32_e32 v3, v26, v0
	v_mul_f32_e32 v5, v27, v0
	v_cvt_pk_bf16_f32 v3, v3, v5
	ds_write_b64 v4, v[2:3] offset:4704
	v_mul_f32_e32 v2, v28, v0
	v_mul_f32_e32 v3, v29, v0
	v_cvt_pk_bf16_f32 v2, v2, v3
	v_mul_f32_e32 v3, v30, v0
	v_mul_f32_e32 v0, v31, v0
	s_lshl_b32 s4, s44, 1
	v_cvt_pk_bf16_f32 v3, v3, v0
	v_lshrrev_b32_e32 v6, 3, v197
	v_lshlrev_b32_e32 v0, 4, v201
	s_add_u32 s4, s92, s4
	ds_write_b64 v4, v[2:3] offset:4720
	v_and_b32_e32 v0, 0x70, v0
	s_addc_u32 s5, s93, 0
	v_mul_u32_u24_e32 v2, 0x90, v6
	s_waitcnt lgkmcnt(0)
	v_lshl_add_u64 v[10:11], s[4:5], 0, v[0:1]
	v_add3_u32 v0, s6, v0, v2
	ds_read_b128 v[2:5], v0
	v_or_b32_e32 v12, s25, v6
	v_lshlrev_b64 v[6:7], 11, v[12:13]
	v_lshl_add_u64 v[14:15], v[10:11], 0, v[6:7]
	ds_read_b128 v[6:9], v0 offset:1152
	s_waitcnt lgkmcnt(1)
	global_store_dwordx4 v[14:15], v[2:5], off
	s_cmp_lt_i32 s94, 8
	v_readlane_b32 s6, v254, 39
	v_or_b32_e32 v2, 8, v12
	v_mov_b32_e32 v3, s28
	v_lshlrev_b64 v[2:3], 11, v[2:3]
	v_lshl_add_u64 v[2:3], v[10:11], 0, v[2:3]
	s_waitcnt lgkmcnt(0)
	global_store_dwordx4 v[2:3], v[6:9], off
	ds_read_b128 v[2:5], v0 offset:2304
	s_cselect_b64 s[4:5], -1, 0
	v_or_b32_e32 v6, 16, v12
	v_mov_b32_e32 v7, s28
	v_lshlrev_b64 v[6:7], 11, v[6:7]
	v_lshl_add_u64 v[14:15], v[10:11], 0, v[6:7]
	ds_read_b128 v[6:9], v0 offset:3456
	s_waitcnt lgkmcnt(1)
	global_store_dwordx4 v[14:15], v[2:5], off
	v_readlane_b32 s7, v254, 40
	s_and_b64 s[4:5], s[6:7], s[4:5]
	v_or_b32_e32 v2, 24, v12
	v_mov_b32_e32 v3, s28
	v_lshlrev_b64 v[2:3], 11, v[2:3]
	v_lshl_add_u64 v[2:3], v[10:11], 0, v[2:3]
	s_waitcnt lgkmcnt(0)
	global_store_dwordx4 v[2:3], v[6:9], off
	ds_read_b128 v[2:5], v0 offset:4608
	s_mov_b32 s45, 0x12000
	v_or_b32_e32 v6, 32, v12
	v_mov_b32_e32 v7, s28
	v_lshlrev_b64 v[6:7], 11, v[6:7]
	v_lshl_add_u64 v[14:15], v[10:11], 0, v[6:7]
	ds_read_b128 v[6:9], v0 offset:5760
	s_waitcnt lgkmcnt(1)
	global_store_dwordx4 v[14:15], v[2:5], off
	s_andn2_b64 vcc, exec, s[4:5]
	s_nop 0
	v_or_b32_e32 v2, 40, v12
	v_mov_b32_e32 v3, s28
	v_lshlrev_b64 v[2:3], 11, v[2:3]
	v_lshl_add_u64 v[2:3], v[10:11], 0, v[2:3]
	s_waitcnt lgkmcnt(0)
	global_store_dwordx4 v[2:3], v[6:9], off
	ds_read_b128 v[2:5], v0 offset:6912
	s_nop 0
	v_or_b32_e32 v6, 48, v12
	v_mov_b32_e32 v7, s28
	v_lshlrev_b64 v[6:7], 11, v[6:7]
	v_lshl_add_u64 v[14:15], v[10:11], 0, v[6:7]
	ds_read_b128 v[6:9], v0 offset:8064
	v_or_b32_e32 v12, 56, v12
	s_waitcnt lgkmcnt(1)
	global_store_dwordx4 v[14:15], v[2:5], off
	s_nop 1
	v_lshlrev_b64 v[2:3], 11, v[12:13]
	v_lshl_add_u64 v[2:3], v[10:11], 0, v[2:3]
	s_waitcnt lgkmcnt(0)
	global_store_dwordx4 v[2:3], v[6:9], off
	s_barrier
	s_cbranch_vccnz .LBB0_411
	s_waitcnt vmcnt(10)
	v_mov_b32_e32 v181, v244
	s_ashr_i32 s18, s94, 2
	v_readfirstlane_b32 s4, v181
	s_ashr_i32 s14, s4, 6
	s_and_b32 s5, s14, 3
	s_or_b32 s15, s5, s23
	s_lshl_b32 s5, s22, 7
	s_ashr_i32 s4, s4, 2
	s_and_b32 s5, s5, 0x80
	s_andn2_b32 s4, s4, 63
	s_add_i32 s4, s4, s5
	s_lshl_b32 s6, s18, 8
	s_ashr_i32 s7, s6, 31
	s_ashr_i32 s5, s4, 31
	s_lshl_b32 s8, s15, 2
	s_add_u32 s4, s6, s4
	v_mov_b32_e32 v0, s8
	s_addc_u32 s5, s7, s5
	global_load_dword v6, v0, s[12:13]
	s_add_u32 s12, s4, 0x4000
	s_addc_u32 s13, s5, 0
	s_cmpk_gt_i32 s18, 0xffbf
	s_cselect_b64 s[4:5], -1, 0
	s_and_b64 s[8:9], s[4:5], exec
	s_movk_i32 s8, 0x4100
	s_cselect_b32 s8, 0x4000, s8
	s_add_u32 s8, s8, s6
	s_addc_u32 s9, 0, s7
	s_lshl_b32 s80, s24, 1
	s_lshl_b32 s16, s15, 7
	v_ashrrev_i32_e32 v2, 3, v181
	s_add_u32 s16, s82, s16
	v_ashrrev_i32_e32 v3, 31, v2
	s_addc_u32 s17, s83, 0
	v_lshl_add_u64 v[4:5], s[8:9], 0, v[2:3]
	v_mov_b64_e32 v[8:9], s[82:83]
	v_lshlrev_b32_e32 v0, 3, v181
	s_cmpk_lt_i32 s18, 0xffc0
	v_mad_u64_u32 v[10:11], s[18:19], v4, s85, v[8:9]
	v_and_b32_e32 v0, 56, v0
	v_mad_i32_i24 v11, v5, s85, v11
	v_lshl_add_u64 v[4:5], v[10:11], 0, s[80:81]
	v_lshlrev_b32_e32 v0, 1, v0
	v_lshl_add_u64 v[4:5], v[4:5], 0, v[0:1]
	global_load_dwordx4 v[130:133], v[4:5], off offset:1024
	global_load_dwordx4 v[134:137], v[4:5], off offset:1280
	v_lshl_add_u64 v[4:5], v[2:3], 0, 64
	v_lshl_add_u64 v[10:11], v[4:5], 0, s[8:9]
	v_mad_u64_u32 v[8:9], s[8:9], v10, s85, v[8:9]
	v_mad_i32_i24 v9, v11, s85, v9
	v_bfe_u32 v200, v181, 5, 1
	v_lshl_add_u64 v[8:9], v[8:9], 0, s[80:81]
	v_and_b32_e32 v183, 31, v181
	v_lshl_add_u64 v[8:9], v[8:9], 0, v[0:1]
	v_lshlrev_b32_e32 v178, 4, v200
	v_mov_b32_e32 v179, v1
	global_load_dwordx4 v[158:161], v[8:9], off offset:1024
	global_load_dwordx4 v[170:173], v[8:9], off offset:1280
	v_or_b32_e32 v7, s12, v183
	v_lshl_add_u64 v[8:9], s[16:17], 0, v[178:179]
	v_mad_u64_u32 v[8:9], s[8:9], v7, s85, v[8:9]
	v_mad_i32_i24 v9, s13, v238, v9
	s_mov_b32 s8, 0x28000
	global_load_dwordx4 v[138:141], v[8:9], off
	global_load_dwordx4 v[142:145], v[8:9], off offset:32
	global_load_dwordx4 v[146:149], v[8:9], off offset:64
	global_load_dwordx4 v[150:153], v[8:9], off offset:96
	v_add_co_u32_e32 v8, vcc, s8, v8
	v_mul_lo_u32 v7, v2, s89
	s_nop 0
	v_addc_co_u32_e32 v9, vcc, 0, v9, vcc
	global_load_dwordx4 v[154:157], v[8:9], off
	global_load_dwordx4 v[162:165], v[8:9], off offset:32
	global_load_dwordx4 v[166:169], v[8:9], off offset:64
	global_load_dwordx4 v[174:177], v[8:9], off offset:96
	v_add3_u32 v203, 0, v7, v0
	s_waitcnt vmcnt(8)
	ds_write_b128 v203, v[130:133]
	ds_write_b128 v203, v[134:137] offset:18432
	ds_write_b128 v203, v[158:161] offset:9216
	ds_write_b128 v203, v[170:173] offset:27648
	s_cbranch_scc1 .LBB0_398
	s_add_u32 s6, s6, 0x4080
	s_addc_u32 s7, s7, 0
	v_lshl_add_u64 v[2:3], s[6:7], 0, v[2:3]
	v_mov_b64_e32 v[8:9], s[82:83]
	v_mad_u64_u32 v[10:11], s[8:9], v2, s85, v[8:9]
	v_mad_i32_i24 v11, v3, s85, v11
	v_lshl_add_u64 v[2:3], v[10:11], 0, s[80:81]
	v_lshl_add_u64 v[2:3], v[2:3], 0, v[0:1]
	global_load_dwordx4 v[130:133], v[2:3], off offset:1024
	global_load_dwordx4 v[134:137], v[2:3], off offset:1280
	v_lshl_add_u64 v[2:3], v[4:5], 0, s[6:7]
	v_mad_u64_u32 v[4:5], s[6:7], v2, s85, v[8:9]
	v_mad_i32_i24 v5, v3, s85, v5
	v_lshl_add_u64 v[2:3], v[4:5], 0, s[80:81]
	v_lshl_add_u64 v[2:3], v[2:3], 0, v[0:1]
	global_load_dwordx4 v[158:161], v[2:3], off offset:1024
	global_load_dwordx4 v[170:173], v[2:3], off offset:1280
